# diff-attention: K/V tiles staged by LDS-DMA (global_load_lds_dwordx4 into the same padded layout) instead of VGPR loads + ds_write_b128
# speedup vs baseline: 1.0161x; 1.0161x over previous
.LBB0_358:
	s_lshl_b64 s[0:1], s[0:1], 1
	v_lshl_add_u64 v[2:3], v[166:167], 0, s[0:1]
	global_load_dwordx4 v[98:101], v[2:3], off
	global_load_dwordx4 v[102:105], v[2:3], off offset:32
	global_load_dwordx4 v[106:109], v[2:3], off offset:64
	global_load_dwordx4 v[110:113], v[2:3], off offset:96
	v_mbcnt_lo_u32_b32 v28, -1, 0
	v_mbcnt_hi_u32_b32 v28, -1, v28
	s_xor_b64 s[8:9], s[8:9], -1
	v_add_u32_e32 v12, s83, v28
	v_ashrrev_i32_e32 v0, 31, v12
	v_lshrrev_b32_e32 v0, 29, v0
	v_add_u32_e32 v0, v12, v0
	v_ashrrev_i32_e32 v231, 3, v0
	v_and_b32_e32 v0, -8, v0
	v_sub_u32_e32 v29, v12, v0
	v_lshlrev_b32_e32 v2, 3, v29
	v_ashrrev_i32_e32 v16, 3, v12
	v_add_u32_e32 v12, 0x200, v12
	s_add_u32 s0, s23, s0
	v_ashrrev_i32_e32 v3, 31, v2
	v_lshlrev_b32_e32 v0, 4, v28
	v_ashrrev_i32_e32 v20, 3, v12
	s_addc_u32 s1, s24, s1
	v_lshlrev_b64 v[2:3], 1, v[2:3]
	v_and_b32_e32 v0, 0x70, v0
	v_ashrrev_i32_e32 v17, 31, v16
	v_ashrrev_i32_e32 v21, 31, v20
	v_lshl_add_u64 v[168:169], s[0:1], 0, v[2:3]
	v_lshl_add_u64 v[170:171], s[6:7], 0, v[0:1]
	v_lshlrev_b64 v[172:173], 15, v[16:17]
	v_lshlrev_b64 v[174:175], 15, v[20:21]
	s_mov_b32 s98, 0x1c71c71d
	s_add_i32 s99, s83, 0
	v_add_u32_e32 v4, s99, v28
	v_add_u32_e32 v5, 0xfffffdc0, v4
	v_cmp_gt_u32_e32 vcc, 0x240, v4
	v_mov_b32_e32 v9, 0x8000
	v_mov_b32_e32 v10, 0x9000
	v_cndmask_b32_e32 v6, v5, v4, vcc
	v_mul_hi_u32 v7, v6, s98
	v_mul_u32_u24_e32 v8, 9, v7
	v_sub_u32_e32 v8, v6, v8
	v_min_u32_e32 v8, 7, v8
	v_lshlrev_b32_e32 v12, 4, v8
	v_mov_b32_e32 v14, 0x800
	v_cndmask_b32_e32 v14, 0, v14, vcc
	v_add_u32_e32 v12, v12, v14
	v_mov_b32_e32 v13, 0
	v_cndmask_b32_e32 v9, v9, v10, vcc
	v_mad_u64_u32 v[10:11], s[100:101], v7, v9, v[12:13]
	v_lshl_add_u64 v[4:5], s[0:1], 0, v[10:11]
	v_lshl_add_u64 v[6:7], s[6:7], 0, v[10:11]
	v_cndmask_b32_e32 v114, v6, v4, vcc
	v_cndmask_b32_e32 v115, v7, v5, vcc
	v_mov_b32_e32 v9, 0x80
	v_mov_b32_e32 v10, 0x240000
	v_cndmask_b32_e32 v122, v9, v10, vcc
	s_add_i32 s99, s83, 512
	v_add_u32_e32 v4, s99, v28
	v_add_u32_e32 v5, 0xfffffdc0, v4
	v_cmp_gt_u32_e32 vcc, 0x240, v4
	v_mov_b32_e32 v9, 0x8000
	v_mov_b32_e32 v10, 0x9000
	v_cndmask_b32_e32 v6, v5, v4, vcc
	v_mul_hi_u32 v7, v6, s98
	v_mul_u32_u24_e32 v8, 9, v7
	v_sub_u32_e32 v8, v6, v8
	v_min_u32_e32 v8, 7, v8
	v_lshlrev_b32_e32 v12, 4, v8
	v_mov_b32_e32 v14, 0x800
	v_cndmask_b32_e32 v14, 0, v14, vcc
	v_add_u32_e32 v12, v12, v14
	v_mov_b32_e32 v13, 0
	v_cndmask_b32_e32 v9, v9, v10, vcc
	v_mad_u64_u32 v[10:11], s[100:101], v7, v9, v[12:13]
	v_lshl_add_u64 v[4:5], s[0:1], 0, v[10:11]
	v_lshl_add_u64 v[6:7], s[6:7], 0, v[10:11]
	v_cndmask_b32_e32 v116, v6, v4, vcc
	v_cndmask_b32_e32 v117, v7, v5, vcc
	v_mov_b32_e32 v9, 0x80
	v_mov_b32_e32 v10, 0x240000
	v_cndmask_b32_e32 v123, v9, v10, vcc
	s_add_i32 s99, s83, 1024
	v_add_u32_e32 v4, s99, v28
	v_add_u32_e32 v5, 0xfffffdc0, v4
	v_cmp_gt_u32_e32 vcc, 0x240, v4
	v_mov_b32_e32 v9, 0x8000
	v_mov_b32_e32 v10, 0x9000
	v_cndmask_b32_e32 v6, v5, v4, vcc
	v_mul_hi_u32 v7, v6, s98
	v_mul_u32_u24_e32 v8, 9, v7
	v_sub_u32_e32 v8, v6, v8
	v_min_u32_e32 v8, 7, v8
	v_lshlrev_b32_e32 v12, 4, v8
	v_mov_b32_e32 v14, 0x800
	v_cndmask_b32_e32 v14, 0, v14, vcc
	v_add_u32_e32 v12, v12, v14
	v_mov_b32_e32 v13, 0
	v_cndmask_b32_e32 v9, v9, v10, vcc
	v_mad_u64_u32 v[10:11], s[100:101], v7, v9, v[12:13]
	v_lshl_add_u64 v[4:5], s[0:1], 0, v[10:11]
	v_lshl_add_u64 v[6:7], s[6:7], 0, v[10:11]
	v_cndmask_b32_e32 v118, v6, v4, vcc
	v_cndmask_b32_e32 v119, v7, v5, vcc
	v_mov_b32_e32 v9, 0x80
	v_mov_b32_e32 v10, 0x240000
	v_cndmask_b32_e32 v124, v9, v10, vcc
	s_add_i32 s99, s83, 1536
	v_add_u32_e32 v4, s99, v28
	v_add_u32_e32 v5, 0xfffffdc0, v4
	v_cmp_gt_u32_e32 vcc, 0x240, v4
	v_mov_b32_e32 v9, 0x8000
	v_mov_b32_e32 v10, 0x9000
	v_cndmask_b32_e32 v6, v5, v4, vcc
	v_mul_hi_u32 v7, v6, s98
	v_mul_u32_u24_e32 v8, 9, v7
	v_sub_u32_e32 v8, v6, v8
	v_min_u32_e32 v8, 7, v8
	v_lshlrev_b32_e32 v12, 4, v8
	v_mov_b32_e32 v14, 0x800
	v_cndmask_b32_e32 v14, 0, v14, vcc
	v_add_u32_e32 v12, v12, v14
	v_mov_b32_e32 v13, 0
	v_cndmask_b32_e32 v9, v9, v10, vcc
	v_mad_u64_u32 v[10:11], s[100:101], v7, v9, v[12:13]
	v_lshl_add_u64 v[4:5], s[0:1], 0, v[10:11]
	v_lshl_add_u64 v[6:7], s[6:7], 0, v[10:11]
	v_cndmask_b32_e32 v120, v6, v4, vcc
	v_cndmask_b32_e32 v121, v7, v5, vcc
	v_mov_b32_e32 v9, 0x80
	v_mov_b32_e32 v10, 0x240000
	v_cndmask_b32_e32 v125, v9, v10, vcc
	s_mov_b32 s101, 0
	s_bitcmp1_b32 s101, 0
	s_cselect_b32 s98, 0x6c00, 0
	s_lshl_b32 s99, s83, 4
	s_add_i32 s98, s98, s99
	v_mad_u64_u32 v[204:205], vcc, v122, s101, v[114:115]
	s_mov_b32 m0, s98
	v_mad_u64_u32 v[206:207], vcc, v123, s101, v[116:117]
	global_load_lds_dwordx4 v[204:205], off
	s_add_i32 m0, s98, 0x2000
	v_mad_u64_u32 v[208:209], vcc, v124, s101, v[118:119]
	global_load_lds_dwordx4 v[206:207], off
	s_add_i32 m0, s98, 0x4000
	s_cmp_ge_u32 s83, 0xc0
	global_load_lds_dwordx4 v[208:209], off
	s_cbranch_scc1 .Ldma_p0
	v_mad_u64_u32 v[210:211], vcc, v125, s101, v[120:121]
	s_add_i32 m0, s98, 0x6000
	s_nop 0
	global_load_lds_dwordx4 v[210:211], off
.Ldma_p0:
	v_add_u32_e32 v17, 64, v231
	v_mad_i64_i32 v[4:5], s[4:5], v231, s87, v[168:169]
	v_lshl_add_u64 v[18:19], v[170:171], 0, v[172:173]
	v_lshl_add_u64 v[22:23], v[170:171], 0, v[174:175]
	v_mad_i64_i32 v[24:25], s[4:5], v17, s87, v[168:169]
	v_add_u32_e32 v17, 0x80, v231
	s_nop 0
	v_mad_i64_i32 v[26:27], s[4:5], v17, s87, v[168:169]
	v_add_u32_e32 v17, 0xc0, v231
	v_mov_b64_e32 v[18:19], s[0:1]
	v_mad_i64_i32 v[18:19], s[0:1], v17, s87, v[18:19]
	v_lshl_add_u64 v[2:3], v[18:19], 0, v[2:3]
	v_lshl_add_u64 v[18:19], s[6:7], 0, v[172:173]
	v_lshl_add_u64 v[18:19], v[18:19], 0, v[0:1]
	v_lshl_add_u64 v[22:23], s[6:7], 0, v[174:175]
	v_lshl_add_u64 v[22:23], v[22:23], 0, v[0:1]
	v_lshlrev_b32_e32 v18, 1, v28
	v_lshrrev_b32_e32 v19, 1, v28
	v_and_b32_e32 v22, 19, v28
	v_and_b32_e32 v18, 8, v18
	v_and_b32_e32 v19, 4, v19
	v_add_u32_e32 v234, 0, v0
	v_or3_b32 v0, v18, v22, v19
	v_mul_lo_u32 v237, v20, s86
	v_mul_lo_u32 v19, v231, s86
	v_lshlrev_b32_e32 v20, 4, v29
	v_mov_b32_e32 v17, s77
	v_mul_lo_u32 v235, v16, s86
	v_add3_u32 v239, 0, v19, v20
	v_bfe_u32 v23, v28, 5, 1
	v_add_u32_e32 v16, v234, v235
	v_add_u32_e32 v18, v234, v237
	v_and_b32_e32 v21, 31, v28
	v_lshlrev_b32_e32 v232, 4, v23
	v_lshlrev_b32_e32 v23, 3, v23
	v_mov_b32_e32 v2, v1
	v_mov_b32_e32 v3, v1
	v_mul_u32_u24_e32 v233, 0x90, v21
	v_sub_u32_e32 v236, v21, v23
	v_mul_u32_u24_e32 v238, 0x90, v0
	v_mov_b32_e32 v0, v1
	s_mov_b32 s94, 0
	v_mov_b32_e32 v178, 0
	v_mov_b32_e32 v240, v230
	v_mov_b32_e32 v241, 0
	s_mov_b32 s26, s94
	s_waitcnt vmcnt(0) lgkmcnt(0)
	s_barrier
	ds_read_b32 v176, v17
	v_mov_b32_e32 v14, v1
	v_mov_b32_e32 v15, v1
	v_mov_b32_e32 v4, v1
	v_mov_b32_e32 v5, v1
	v_mov_b32_e32 v6, v1
	v_mov_b32_e32 v7, v1
	v_mov_b32_e32 v8, v1
	v_mov_b32_e32 v9, v1
	v_mov_b32_e32 v10, v1
	v_mov_b32_e32 v11, v1
	v_mov_b32_e32 v12, v1
	v_mov_b32_e32 v13, v1
	v_mov_b64_e32 v[64:65], v[14:15]
	v_mov_b64_e32 v[48:49], v[14:15]
	v_mov_b64_e32 v[32:33], v[14:15]
	v_mov_b64_e32 v[62:63], v[12:13]
	v_mov_b64_e32 v[60:61], v[10:11]
	v_mov_b64_e32 v[58:59], v[8:9]
	v_mov_b64_e32 v[56:57], v[6:7]
	v_mov_b64_e32 v[54:55], v[4:5]
	v_mov_b64_e32 v[52:53], v[2:3]
	v_mov_b64_e32 v[50:51], v[0:1]
	v_mov_b64_e32 v[46:47], v[12:13]
	v_mov_b64_e32 v[44:45], v[10:11]
	v_mov_b64_e32 v[42:43], v[8:9]
	v_mov_b64_e32 v[40:41], v[6:7]
	v_mov_b64_e32 v[38:39], v[4:5]
	v_mov_b64_e32 v[36:37], v[2:3]
	v_mov_b64_e32 v[34:35], v[0:1]
	v_mov_b64_e32 v[30:31], v[12:13]
	v_mov_b64_e32 v[28:29], v[10:11]
	v_mov_b64_e32 v[26:27], v[8:9]
	v_mov_b64_e32 v[24:25], v[6:7]
	v_mov_b64_e32 v[22:23], v[4:5]
	v_mov_b64_e32 v[20:21], v[2:3]
	v_mov_b64_e32 v[18:19], v[0:1]
	v_mov_b64_e32 v[16:17], v[14:15]
	v_mov_b64_e32 v[14:15], v[12:13]
	v_mov_b64_e32 v[12:13], v[10:11]
	v_mov_b64_e32 v[10:11], v[8:9]
	v_mov_b64_e32 v[8:9], v[6:7]
	v_mov_b64_e32 v[6:7], v[4:5]
	v_mov_b64_e32 v[4:5], v[2:3]
	v_mov_b64_e32 v[2:3], v[0:1]
.LBB0_359:
	s_add_i32 s27, s26, 1
	s_cmp_lt_u32 s27, s22
	s_cselect_b64 s[10:11], -1, 0
	s_cmp_ge_u32 s27, s22
	s_cbranch_scc1 .LBB0_362
	s_bitcmp1_b32 s27, 0
	s_cselect_b32 s98, 0x6c00, 0
	s_lshl_b32 s99, s83, 4
	s_add_i32 s98, s98, s99
	v_mad_u64_u32 v[204:205], vcc, v122, s27, v[114:115]
	s_mov_b32 m0, s98
	v_mad_u64_u32 v[206:207], vcc, v123, s27, v[116:117]
	global_load_lds_dwordx4 v[204:205], off
	s_add_i32 m0, s98, 0x2000
	v_mad_u64_u32 v[208:209], vcc, v124, s27, v[118:119]
	global_load_lds_dwordx4 v[206:207], off
	s_add_i32 m0, s98, 0x4000
	s_cmp_ge_u32 s83, 0xc0
	global_load_lds_dwordx4 v[208:209], off
	s_cbranch_scc1 .LBB0_362
	v_mad_u64_u32 v[210:211], vcc, v125, s27, v[120:121]
	s_add_i32 m0, s98, 0x6000
	s_nop 0
	global_load_lds_dwordx4 v[210:211], off

.LBB0_372:
	s_or_b64 exec, exec, s[12:13]
	s_andn2_b64 vcc, exec, s[10:11]
	s_waitcnt vmcnt(0) lgkmcnt(0)
	s_barrier
	s_cbranch_vccz .LBB0_375
	s_add_i32 s0, s26, 2
	s_add_i32 s12, s26, 3
	s_cmp_ge_u32 s0, s22
	s_cbranch_scc0 .LBB0_388

.LBB0_375:
	s_cmp_ge_u32 s26, s25
	s_cbranch_scc1 .LBB0_378
	s_add_i32 s100, s26, 2
	s_bitcmp1_b32 s100, 0
	s_cselect_b32 s98, 0x6c00, 0
	s_lshl_b32 s99, s83, 4
	s_add_i32 s98, s98, s99
	v_mad_u64_u32 v[204:205], vcc, v122, s100, v[114:115]
	s_mov_b32 m0, s98
	v_mad_u64_u32 v[206:207], vcc, v123, s100, v[116:117]
	global_load_lds_dwordx4 v[204:205], off
	s_add_i32 m0, s98, 0x2000
	v_mad_u64_u32 v[208:209], vcc, v124, s100, v[118:119]
	global_load_lds_dwordx4 v[206:207], off
	s_add_i32 m0, s98, 0x4000
	s_cmp_ge_u32 s83, 0xc0
	global_load_lds_dwordx4 v[208:209], off
	s_cbranch_scc1 .LBB0_378
	v_mad_u64_u32 v[210:211], vcc, v125, s100, v[120:121]
	s_add_i32 m0, s98, 0x6000
	s_nop 0
	global_load_lds_dwordx4 v[210:211], off

.LBB0_387:
	s_or_b64 exec, exec, s[10:11]
	s_waitcnt vmcnt(0) lgkmcnt(0)
	s_barrier
	s_add_i32 s0, s26, 2
	s_add_i32 s12, s26, 3
	s_cmp_ge_u32 s0, s22
	s_cbranch_scc1 .LBB0_374
.LBB0_388:
	s_cmp_ge_u32 s12, s22
	s_cbranch_scc1 .LBB0_391
	s_bitcmp1_b32 s12, 0
	s_cselect_b32 s98, 0x6c00, 0
	s_lshl_b32 s99, s83, 4
	s_add_i32 s98, s98, s99
	v_mad_u64_u32 v[204:205], vcc, v122, s12, v[114:115]
	s_mov_b32 m0, s98
	v_mad_u64_u32 v[206:207], vcc, v123, s12, v[116:117]
	global_load_lds_dwordx4 v[204:205], off
	s_add_i32 m0, s98, 0x2000
	v_mad_u64_u32 v[208:209], vcc, v124, s12, v[118:119]
	global_load_lds_dwordx4 v[206:207], off
	s_add_i32 m0, s98, 0x4000
	s_cmp_ge_u32 s83, 0xc0
	global_load_lds_dwordx4 v[208:209], off
	s_cbranch_scc1 .LBB0_391
	v_mad_u64_u32 v[210:211], vcc, v125, s12, v[120:121]
	s_add_i32 m0, s98, 0x6000
	s_nop 0
	global_load_lds_dwordx4 v[210:211], off

.LBB0_400:
	s_or_b64 exec, exec, s[10:11]
	s_waitcnt vmcnt(0) lgkmcnt(0)
	s_barrier
	s_addk_i32 s94, 0xc0
	s_cmp_lt_u32 s12, s22
	v_add_u32_e32 v240, 0xffffff40, v240
	s_cbranch_scc0 .LBB0_402
